# grid barrier: buffer_inv sc1 issued right after the arrive atomic instead of after the poll
# speedup vs baseline: 1.0122x; 1.0122x over previous
.LBB0_166:
	s_or_b64 exec, exec, s[4:5]
	buffer_inv sc1
	v_cvt_f32_u32_e32 v4, v0
	s_waitcnt vmcnt(1)
	v_readfirstlane_b32 s4, v3
	s_mov_b32 s20, 1
	v_rcp_iflag_f32_e32 v4, v4
	v_add_u32_e32 v1, s4, v1
	v_mul_f32_e32 v3, 0x4f7ffffe, v4
	v_cvt_u32_f32_e32 v3, v3
	v_sub_u32_e32 v4, 0, v0
	v_mul_lo_u32 v4, v4, v3
	v_mul_hi_u32 v4, v3, v4
	v_add_u32_e32 v3, v3, v4
	v_mul_hi_u32 v3, v1, v3
	v_mul_lo_u32 v4, v3, v0
	v_sub_u32_e32 v4, v1, v4
	v_add_u32_e32 v5, 1, v3
	v_cmp_ge_u32_e32 vcc, v4, v0
	v_add_u32_e32 v1, 1, v1
	s_nop 0
	v_cndmask_b32_e32 v3, v3, v5, vcc
	v_sub_u32_e32 v5, v4, v0
	v_cndmask_b32_e32 v4, v4, v5, vcc
	v_add_u32_e32 v5, 1, v3
	v_cmp_ge_u32_e32 vcc, v4, v0
	s_nop 1
	v_cndmask_b32_e32 v3, v3, v5, vcc
	v_add_u32_e32 v3, 1, v3
	v_mul_lo_u32 v0, v3, v0
	v_cmp_eq_u32_e32 vcc, v1, v0
	s_and_saveexec_b64 s[4:5], vcc
	s_cbranch_execz .LBB0_168
	v_readlane_b32 s6, v255, 37
	s_lshl_b32 s6, s6, 2
	v_readlane_b32 s8, v255, 35
	buffer_wbl2 sc1
	s_waitcnt lgkmcnt(0)
	s_waitcnt vmcnt(0)
	v_readlane_b32 s9, v255, 36
	s_add_u32 s6, s8, s6
	s_addc_u32 s7, s9, 0
	v_mov_b32_e32 v0, 0x3000
	global_store_dword v0, v3, s[6:7] offset:1024 sc1

.LBB0_182:
	s_or_b64 exec, exec, s[4:5]
	s_waitcnt vmcnt(0)
.LBB0_183:
	s_or_b64 exec, exec, s[2:3]
	s_barrier

.LBB0_1365:
	s_or_b64 exec, exec, s[4:5]
	s_waitcnt vmcnt(0)
.LBB0_1366:
	s_or_b64 exec, exec, s[2:3]
	s_barrier

.LBB0_1669:
	s_or_b64 exec, exec, s[4:5]
	s_waitcnt vmcnt(0)
.LBB0_1670:
	s_or_b64 exec, exec, s[0:1]
	s_barrier

.LBB0_1832:
	s_or_b64 exec, exec, s[4:5]
	s_waitcnt vmcnt(0)
.LBB0_1833:
	s_or_b64 exec, exec, s[0:1]
	s_barrier

.LBB0_2271:
	s_or_b64 exec, exec, s[4:5]
	s_waitcnt vmcnt(0)
.LBB0_2272:
	s_or_b64 exec, exec, s[0:1]
	s_barrier

.LBB0_2342:
	s_or_b64 exec, exec, s[2:3]
	buffer_inv sc1
	v_cvt_f32_u32_e32 v4, v0
	s_waitcnt vmcnt(1)
	v_readfirstlane_b32 s2, v3
	s_mov_b32 s18, 1
	v_rcp_iflag_f32_e32 v4, v4
	v_add_u32_e32 v1, s2, v1
	v_mul_f32_e32 v3, 0x4f7ffffe, v4
	v_cvt_u32_f32_e32 v3, v3
	v_sub_u32_e32 v4, 0, v0
	v_mul_lo_u32 v4, v4, v3
	v_mul_hi_u32 v4, v3, v4
	v_add_u32_e32 v3, v3, v4
	v_mul_hi_u32 v3, v1, v3
	v_mul_lo_u32 v4, v3, v0
	v_sub_u32_e32 v4, v1, v4
	v_add_u32_e32 v5, 1, v3
	v_cmp_ge_u32_e32 vcc, v4, v0
	v_add_u32_e32 v1, 1, v1
	s_nop 0
	v_cndmask_b32_e32 v3, v3, v5, vcc
	v_sub_u32_e32 v5, v4, v0
	v_cndmask_b32_e32 v4, v4, v5, vcc
	v_add_u32_e32 v5, 1, v3
	v_cmp_ge_u32_e32 vcc, v4, v0
	s_nop 1
	v_cndmask_b32_e32 v3, v3, v5, vcc
	v_add_u32_e32 v3, 1, v3
	v_mul_lo_u32 v0, v3, v0
	v_cmp_eq_u32_e32 vcc, v1, v0
	s_and_saveexec_b64 s[2:3], vcc
	s_cbranch_execz .LBB0_2344
	v_readlane_b32 s4, v255, 37
	s_lshl_b32 s4, s4, 2
	v_readlane_b32 s6, v255, 35
	buffer_wbl2 sc1
	s_waitcnt lgkmcnt(0)
	s_waitcnt vmcnt(0)
	v_readlane_b32 s7, v255, 36
	s_add_u32 s4, s6, s4
	s_addc_u32 s5, s7, 0
	v_mov_b32_e32 v0, 0x3000
	global_store_dword v0, v3, s[4:5] offset:1024 sc1

.LBB0_2358:
	s_or_b64 exec, exec, s[2:3]
	s_waitcnt vmcnt(0)
.LBB0_2359:
	s_or_b64 exec, exec, s[0:1]
	s_barrier

.LBB0_2424:
	s_or_b64 exec, exec, s[4:5]
	s_waitcnt vmcnt(0)
.LBB0_2425:
	s_or_b64 exec, exec, s[0:1]
	s_barrier

.LBB0_2559:
	s_or_b64 exec, exec, s[2:3]
	s_waitcnt vmcnt(0)
.LBB0_2560:
	s_or_b64 exec, exec, s[0:1]
	s_barrier

.LBB0_2960:
	s_or_b64 exec, exec, s[4:5]
	s_waitcnt vmcnt(0)
.LBB0_2961:
	s_or_b64 exec, exec, s[2:3]
	s_barrier

.LBB0_3047:
	s_or_b64 exec, exec, s[2:3]
	s_waitcnt vmcnt(0)
.LBB0_3048:
	s_or_b64 exec, exec, s[0:1]
	s_barrier

.LBB0_3101:
	s_or_b64 exec, exec, s[4:5]
	s_waitcnt vmcnt(0)
.LBB0_3102:
	s_or_b64 exec, exec, s[0:1]
	s_barrier
